# speedup vs baseline: 1.0150x; 1.0074x over previous
; __device__ __forceinline__ uint4 pk8(f32x4 a, f32x4 b) { return make_uint4(cvt_pk_bf16(a[0], a[1]), cvt_pk_bf16(a[2], a[3]), cvt_pk_bf16(b[0], b[1]), cvt_pk_bf16(b[2], b[3])); }
;     __device__ __forceinline__ void operator()(AccRef acc, const Unit& u, int wr, int wc, int fr, int fq) const {
;         const int pi = u.pn / tpp; bf16_t* base = pi == 0 ? pl[0] : (pi == 1 ? pl[1] : (pi == 2 ? pl[2] : pl[3]));
;         const int cbase = (u.pn - pi * tpp) * 256 + wc * 32 + 8 * fq;
; #pragma unroll
;         for (int ai = 0; ai < 2; ++ai)
; #pragma unroll
;             for (int m = 0; m < 4; ++m) {
;                 const int r = u.pm * 256 + ai * 128 + wr * 64 + m * 16 + fr;
;                 float s = 1.f;
;                 if (SCALE == 1) s = rs[r];
;                 if (SCALE == 2) s = rsqrtf(rs[r] * (1.f / D) + EPS);
;                 bf16_t* rowp = base + (size_t)r * ldc + cbase;
; #pragma unroll
;                 for (int bj = 0; bj < 2; ++bj) *(uint4*)(rowp + bj * 128) = pk8(acc[ai][bj][m][0] * s, acc[ai][bj][m][1] * s);
;             }
.LBB0_107:
	s_cmp_eq_u32 s13, 1
	s_cselect_b32 s99, -1, 0
	s_lshl_b32 s11, s18, 8
	v_add_u32_e32 v138, s11, v158
	v_ashrrev_i32_e32 v139, 31, v138
	v_lshl_add_u64 v[136:137], v[138:139], 2, s[28:29]
	global_load_dword v168, v[136:137], off
	s_lshl_b32 s13, s13, 10
	s_lshl_b32 s18, s50, 8
	s_sub_i32 s13, s18, s13
	v_or_b32_e32 v136, s13, v163
	v_ashrrev_i32_e32 v137, 31, v136
	v_add_u32_e32 v170, s11, v160
	v_lshlrev_b64 v[172:173], 11, v[138:139]
	v_lshl_add_u64 v[136:137], v[136:137], 1, s[20:21]
	v_bfe_i32 v200, v144, 0, 1
	v_and_b32_e32 v200, 0xfffff840, v200
	v_bfe_u32 v201, v146, 1, 1
	v_mul_u32_u24_e32 v201, 0x780, v201
	v_add_u32_e32 v200, v200, v201
	v_and_b32_e32 v201, 1, v146
	v_lshl_add_u32 v200, v201, 6, v200
	v_and_b32_e32 v200, s99, v200
	v_ashrrev_i32_e32 v201, 31, v200
	v_lshl_add_u64 v[136:137], v[200:201], 0, v[136:137]
	v_ashrrev_i32_e32 v171, 31, v170
	v_lshl_add_u64 v[172:173], v[136:137], 0, v[172:173]
	v_lshl_add_u64 v[174:175], v[170:171], 2, s[28:29]
	s_and_b64 vcc, exec, s[4:5]
	s_mov_b32 s50, s10
	s_mov_b32 s18, s12
	s_mov_b64 s[22:23], s[16:17]
	s_mov_b64 s[20:21], s[14:15]
	global_load_dword v178, v[174:175], off
	v_add_u32_e32 v200, s11, v161
	v_ashrrev_i32_e32 v201, 31, v200
	v_lshl_add_u64 v[202:203], v[200:201], 2, s[28:29]
	global_load_dword v180, v[202:203], off
	v_add_u32_e32 v200, s11, v162
	v_ashrrev_i32_e32 v201, 31, v200
	v_lshl_add_u64 v[202:203], v[200:201], 2, s[28:29]
	global_load_dword v182, v[202:203], off
	v_add_u32_e32 v200, 0x80, v138
	v_ashrrev_i32_e32 v201, 31, v200
	v_lshl_add_u64 v[202:203], v[200:201], 2, s[28:29]
	global_load_dword v184, v[202:203], off
	v_add_u32_e32 v200, 0x90, v138
	v_ashrrev_i32_e32 v201, 31, v200
	v_lshl_add_u64 v[202:203], v[200:201], 2, s[28:29]
	global_load_dword v186, v[202:203], off
	v_add_u32_e32 v200, 0xa0, v138
	v_ashrrev_i32_e32 v201, 31, v200
	v_lshl_add_u64 v[202:203], v[200:201], 2, s[28:29]
	global_load_dword v188, v[202:203], off
	v_add_u32_e32 v200, 0xb0, v138
	v_ashrrev_i32_e32 v201, 31, v200
	v_lshl_add_u64 v[202:203], v[200:201], 2, s[28:29]
	global_load_dword v190, v[202:203], off
	s_waitcnt vmcnt(7)
	v_pk_mul_f32 v[126:127], v[126:127], v[168:169] op_sel_hi:[1,0]
	v_pk_mul_f32 v[124:125], v[124:125], v[168:169] op_sel_hi:[1,0]
	v_pk_mul_f32 v[122:123], v[122:123], v[168:169] op_sel_hi:[1,0]
	v_pk_mul_f32 v[120:121], v[120:121], v[168:169] op_sel_hi:[1,0]
	v_pk_mul_f32 v[118:119], v[118:119], v[168:169] op_sel_hi:[1,0]
	v_pk_mul_f32 v[116:117], v[116:117], v[168:169] op_sel_hi:[1,0]
	v_pk_mul_f32 v[176:177], v[114:115], v[168:169] op_sel_hi:[1,0]
	v_pk_mul_f32 v[168:169], v[112:113], v[168:169] op_sel_hi:[1,0]
	v_cvt_pk_bf16_f32 v112, v124, v125
	v_cvt_pk_bf16_f32 v113, v126, v127
	v_cvt_pk_bf16_f32 v114, v120, v121
	v_cvt_pk_bf16_f32 v115, v122, v123
	global_store_dwordx4 v[172:173], v[112:115], off
	s_nop 1
	v_cvt_pk_bf16_f32 v112, v116, v117
	v_cvt_pk_bf16_f32 v113, v118, v119
	v_cvt_pk_bf16_f32 v114, v168, v169
	v_cvt_pk_bf16_f32 v115, v176, v177
	global_store_dwordx4 v[172:173], v[112:115], off offset:256
	v_lshlrev_b64 v[116:117], 11, v[170:171]
	v_add_u32_e32 v114, s11, v161
	v_ashrrev_i32_e32 v115, 31, v114
	v_lshl_add_u64 v[116:117], v[136:137], 0, v[116:117]
	v_lshl_add_u64 v[118:119], v[114:115], 2, s[28:29]
	s_waitcnt vmcnt(8)
	v_pk_mul_f32 v[110:111], v[110:111], v[178:179] op_sel_hi:[1,0]
	v_pk_mul_f32 v[108:109], v[108:109], v[178:179] op_sel_hi:[1,0]
	v_pk_mul_f32 v[106:107], v[106:107], v[178:179] op_sel_hi:[1,0]
	v_pk_mul_f32 v[104:105], v[104:105], v[178:179] op_sel_hi:[1,0]
	v_pk_mul_f32 v[102:103], v[102:103], v[178:179] op_sel_hi:[1,0]
	v_pk_mul_f32 v[100:101], v[100:101], v[178:179] op_sel_hi:[1,0]
	v_pk_mul_f32 v[120:121], v[98:99], v[178:179] op_sel_hi:[1,0]
	v_pk_mul_f32 v[112:113], v[96:97], v[178:179] op_sel_hi:[1,0]
	v_cvt_pk_bf16_f32 v96, v108, v109
	v_cvt_pk_bf16_f32 v97, v110, v111
	v_cvt_pk_bf16_f32 v98, v104, v105
	v_cvt_pk_bf16_f32 v99, v106, v107
	global_store_dwordx4 v[116:117], v[96:99], off
	s_nop 1
	v_cvt_pk_bf16_f32 v96, v100, v101
	v_cvt_pk_bf16_f32 v97, v102, v103
	v_cvt_pk_bf16_f32 v98, v112, v113
	v_cvt_pk_bf16_f32 v99, v120, v121
	global_store_dwordx4 v[116:117], v[96:99], off offset:256
	v_lshlrev_b64 v[100:101], 11, v[114:115]
	v_add_u32_e32 v98, s11, v162
	v_ashrrev_i32_e32 v99, 31, v98
	v_lshl_add_u64 v[100:101], v[136:137], 0, v[100:101]
	v_lshl_add_u64 v[102:103], v[98:99], 2, s[28:29]
	s_waitcnt vmcnt(9)
	v_pk_mul_f32 v[94:95], v[94:95], v[180:181] op_sel_hi:[1,0]
	v_pk_mul_f32 v[92:93], v[92:93], v[180:181] op_sel_hi:[1,0]
	v_pk_mul_f32 v[90:91], v[90:91], v[180:181] op_sel_hi:[1,0]
	v_pk_mul_f32 v[88:89], v[88:89], v[180:181] op_sel_hi:[1,0]
	v_pk_mul_f32 v[86:87], v[86:87], v[180:181] op_sel_hi:[1,0]
	v_pk_mul_f32 v[84:85], v[84:85], v[180:181] op_sel_hi:[1,0]
	v_pk_mul_f32 v[104:105], v[82:83], v[180:181] op_sel_hi:[1,0]
	v_pk_mul_f32 v[96:97], v[80:81], v[180:181] op_sel_hi:[1,0]
	v_cvt_pk_bf16_f32 v80, v92, v93
	v_cvt_pk_bf16_f32 v81, v94, v95
	v_cvt_pk_bf16_f32 v82, v88, v89
	v_cvt_pk_bf16_f32 v83, v90, v91
	global_store_dwordx4 v[100:101], v[80:83], off
	s_nop 1
	v_cvt_pk_bf16_f32 v80, v84, v85
	v_cvt_pk_bf16_f32 v81, v86, v87
	v_cvt_pk_bf16_f32 v82, v96, v97
	v_cvt_pk_bf16_f32 v83, v104, v105
	global_store_dwordx4 v[100:101], v[80:83], off offset:256
	v_lshlrev_b64 v[84:85], 11, v[98:99]
	v_add_u32_e32 v82, 0x80, v138
	v_ashrrev_i32_e32 v83, 31, v82
	v_lshl_add_u64 v[84:85], v[136:137], 0, v[84:85]
	v_lshl_add_u64 v[86:87], v[82:83], 2, s[28:29]
	s_waitcnt vmcnt(10)
; __device__ __forceinline__ uint4 pk8(f32x4 a, f32x4 b) { return make_uint4(cvt_pk_bf16(a[0], a[1]), cvt_pk_bf16(a[2], a[3]), cvt_pk_bf16(b[0], b[1]), cvt_pk_bf16(b[2], b[3])); }
;     __device__ __forceinline__ void operator()(AccRef acc, const Unit& u, int wr, int wc, int fr, int fq) const {
;         const int pi = u.pn / tpp; bf16_t* base = pi == 0 ? pl[0] : (pi == 1 ? pl[1] : (pi == 2 ? pl[2] : pl[3]));
;         const int cbase = (u.pn - pi * tpp) * 256 + wc * 32 + 8 * fq;
; #pragma unroll
;         for (int ai = 0; ai < 2; ++ai)
; #pragma unroll
;             for (int m = 0; m < 4; ++m) {
;                 const int r = u.pm * 256 + ai * 128 + wr * 64 + m * 16 + fr;
;                 float s = 1.f;
;                 if (SCALE == 1) s = rs[r];
;                 if (SCALE == 2) s = rsqrtf(rs[r] * (1.f / D) + EPS);
;                 bf16_t* rowp = base + (size_t)r * ldc + cbase;
; #pragma unroll
;                 for (int bj = 0; bj < 2; ++bj) *(uint4*)(rowp + bj * 128) = pk8(acc[ai][bj][m][0] * s, acc[ai][bj][m][1] * s);
;             }
	v_pk_mul_f32 v[78:79], v[78:79], v[182:183] op_sel_hi:[1,0]
	v_pk_mul_f32 v[76:77], v[76:77], v[182:183] op_sel_hi:[1,0]
	v_pk_mul_f32 v[74:75], v[74:75], v[182:183] op_sel_hi:[1,0]
	v_pk_mul_f32 v[72:73], v[72:73], v[182:183] op_sel_hi:[1,0]
	v_pk_mul_f32 v[70:71], v[70:71], v[182:183] op_sel_hi:[1,0]
	v_pk_mul_f32 v[68:69], v[68:69], v[182:183] op_sel_hi:[1,0]
	v_pk_mul_f32 v[88:89], v[66:67], v[182:183] op_sel_hi:[1,0]
	v_pk_mul_f32 v[80:81], v[64:65], v[182:183] op_sel_hi:[1,0]
	v_cvt_pk_bf16_f32 v64, v76, v77
	v_cvt_pk_bf16_f32 v65, v78, v79
	v_cvt_pk_bf16_f32 v66, v72, v73
	v_cvt_pk_bf16_f32 v67, v74, v75
	global_store_dwordx4 v[84:85], v[64:67], off
	s_nop 1
	v_cvt_pk_bf16_f32 v64, v68, v69
	v_cvt_pk_bf16_f32 v65, v70, v71
	v_cvt_pk_bf16_f32 v66, v80, v81
	v_cvt_pk_bf16_f32 v67, v88, v89
	global_store_dwordx4 v[84:85], v[64:67], off offset:256
	v_lshlrev_b64 v[68:69], 11, v[82:83]
	v_add_u32_e32 v66, 0x90, v138
	v_ashrrev_i32_e32 v67, 31, v66
	v_lshl_add_u64 v[68:69], v[136:137], 0, v[68:69]
	v_lshl_add_u64 v[70:71], v[66:67], 2, s[28:29]
	s_waitcnt vmcnt(11)
	v_pk_mul_f32 v[62:63], v[62:63], v[184:185] op_sel_hi:[1,0]
	v_pk_mul_f32 v[60:61], v[60:61], v[184:185] op_sel_hi:[1,0]
	v_pk_mul_f32 v[58:59], v[58:59], v[184:185] op_sel_hi:[1,0]
	v_pk_mul_f32 v[56:57], v[56:57], v[184:185] op_sel_hi:[1,0]
	v_pk_mul_f32 v[54:55], v[54:55], v[184:185] op_sel_hi:[1,0]
	v_pk_mul_f32 v[52:53], v[52:53], v[184:185] op_sel_hi:[1,0]
	v_pk_mul_f32 v[72:73], v[50:51], v[184:185] op_sel_hi:[1,0]
	v_pk_mul_f32 v[64:65], v[48:49], v[184:185] op_sel_hi:[1,0]
	v_cvt_pk_bf16_f32 v48, v60, v61
	v_cvt_pk_bf16_f32 v49, v62, v63
	v_cvt_pk_bf16_f32 v50, v56, v57
	v_cvt_pk_bf16_f32 v51, v58, v59
	global_store_dwordx4 v[68:69], v[48:51], off
	s_nop 1
	v_cvt_pk_bf16_f32 v48, v52, v53
	v_cvt_pk_bf16_f32 v49, v54, v55
	v_cvt_pk_bf16_f32 v50, v64, v65
	v_cvt_pk_bf16_f32 v51, v72, v73
	global_store_dwordx4 v[68:69], v[48:51], off offset:256
	v_lshlrev_b64 v[52:53], 11, v[66:67]
	v_add_u32_e32 v50, 0xa0, v138
	v_ashrrev_i32_e32 v51, 31, v50
	v_lshl_add_u64 v[52:53], v[136:137], 0, v[52:53]
	v_lshl_add_u64 v[54:55], v[50:51], 2, s[28:29]
	s_waitcnt vmcnt(12)
	v_pk_mul_f32 v[46:47], v[46:47], v[186:187] op_sel_hi:[1,0]
	v_pk_mul_f32 v[44:45], v[44:45], v[186:187] op_sel_hi:[1,0]
	v_pk_mul_f32 v[42:43], v[42:43], v[186:187] op_sel_hi:[1,0]
	v_pk_mul_f32 v[40:41], v[40:41], v[186:187] op_sel_hi:[1,0]
	v_pk_mul_f32 v[38:39], v[38:39], v[186:187] op_sel_hi:[1,0]
	v_pk_mul_f32 v[36:37], v[36:37], v[186:187] op_sel_hi:[1,0]
	v_pk_mul_f32 v[56:57], v[34:35], v[186:187] op_sel_hi:[1,0]
	v_pk_mul_f32 v[48:49], v[32:33], v[186:187] op_sel_hi:[1,0]
	v_cvt_pk_bf16_f32 v32, v44, v45
	v_cvt_pk_bf16_f32 v33, v46, v47
	v_cvt_pk_bf16_f32 v34, v40, v41
	v_cvt_pk_bf16_f32 v35, v42, v43
	global_store_dwordx4 v[52:53], v[32:35], off
	s_nop 1
	v_cvt_pk_bf16_f32 v32, v36, v37
	v_cvt_pk_bf16_f32 v33, v38, v39
	v_cvt_pk_bf16_f32 v34, v48, v49
	v_cvt_pk_bf16_f32 v35, v56, v57
	global_store_dwordx4 v[52:53], v[32:35], off offset:256
	v_lshlrev_b64 v[36:37], 11, v[50:51]
	v_add_u32_e32 v34, 0xb0, v138
	v_ashrrev_i32_e32 v35, 31, v34
	v_lshl_add_u64 v[36:37], v[136:137], 0, v[36:37]
	v_lshl_add_u64 v[38:39], v[34:35], 2, s[28:29]
	s_waitcnt vmcnt(13)
	v_pk_mul_f32 v[30:31], v[30:31], v[188:189] op_sel_hi:[1,0]
	v_pk_mul_f32 v[28:29], v[28:29], v[188:189] op_sel_hi:[1,0]
	v_pk_mul_f32 v[26:27], v[26:27], v[188:189] op_sel_hi:[1,0]
	v_pk_mul_f32 v[24:25], v[24:25], v[188:189] op_sel_hi:[1,0]
	v_pk_mul_f32 v[22:23], v[22:23], v[188:189] op_sel_hi:[1,0]
	v_pk_mul_f32 v[20:21], v[20:21], v[188:189] op_sel_hi:[1,0]
	v_pk_mul_f32 v[40:41], v[18:19], v[188:189] op_sel_hi:[1,0]
	v_pk_mul_f32 v[32:33], v[16:17], v[188:189] op_sel_hi:[1,0]
	v_cvt_pk_bf16_f32 v16, v28, v29
	v_cvt_pk_bf16_f32 v17, v30, v31
	v_cvt_pk_bf16_f32 v18, v24, v25
	v_cvt_pk_bf16_f32 v19, v26, v27
	global_store_dwordx4 v[36:37], v[16:19], off
	s_nop 1
	v_cvt_pk_bf16_f32 v16, v20, v21
	v_cvt_pk_bf16_f32 v17, v22, v23
	v_cvt_pk_bf16_f32 v18, v32, v33
	v_cvt_pk_bf16_f32 v19, v40, v41
	global_store_dwordx4 v[36:37], v[16:19], off offset:256
	s_waitcnt vmcnt(14)
	v_pk_mul_f32 v[14:15], v[14:15], v[190:191] op_sel_hi:[1,0]
	v_lshlrev_b64 v[18:19], 11, v[34:35]
	v_lshl_add_u64 v[18:19], v[136:137], 0, v[18:19]
	v_pk_mul_f32 v[12:13], v[12:13], v[190:191] op_sel_hi:[1,0]
	v_pk_mul_f32 v[10:11], v[10:11], v[190:191] op_sel_hi:[1,0]
	v_pk_mul_f32 v[8:9], v[8:9], v[190:191] op_sel_hi:[1,0]
	v_pk_mul_f32 v[6:7], v[6:7], v[190:191] op_sel_hi:[1,0]
	v_pk_mul_f32 v[4:5], v[4:5], v[190:191] op_sel_hi:[1,0]
	v_pk_mul_f32 v[20:21], v[2:3], v[190:191] op_sel_hi:[1,0]
	v_pk_mul_f32 v[16:17], v[0:1], v[190:191] op_sel_hi:[1,0]
	v_cvt_pk_bf16_f32 v0, v12, v13
	v_cvt_pk_bf16_f32 v1, v14, v15
	v_cvt_pk_bf16_f32 v2, v8, v9
	v_cvt_pk_bf16_f32 v3, v10, v11
	global_store_dwordx4 v[18:19], v[0:3], off
	s_nop 1
	v_cvt_pk_bf16_f32 v0, v4, v5
	v_cvt_pk_bf16_f32 v1, v6, v7
	v_cvt_pk_bf16_f32 v2, v16, v17
	v_cvt_pk_bf16_f32 v3, v20, v21
	global_store_dwordx4 v[18:19], v[0:3], off offset:256
	s_cbranch_vccnz .LBB0_126

; __device__ void phase_na(const Params& P, unsigned char* smem) {
;     const int tid = threadIdx.x, lane = tid & 63, wid = tid >> 6, l15 = lane & 15, l4 = lane >> 4;
;     float* rpb_s = (float*)smem;
;     for (int i = tid; i < 8 * 15 * 31; i += 512) rpb_s[i] = P.in[I_RPB][i];
;     __syncthreads();
;     const bf16_t* Qp = (const bf16_t*)(P.ws + O_R2);
;     const bf16_t* Kp = (const bf16_t*)P.out;
;     const bf16_t* Vt = (const bf16_t*)((const unsigned char*)P.out + 128 * MiB);
;     const int h = blockIdx.x & 7, nbh = ((int)gridDim.x - h + 7) >> 3;
;     const float scale = 0.08838834764831845f;
;     for (int uu = ((int)blockIdx.x >> 3) * 8 + wid; uu < 2048; uu += nbh * 8) {
;         const int grow = uu >> 2, j = uu & 3;
;         int rows, r, tokbase;
;         if (grow < 256) { rows = 256; r = grow; tokbase = 0; } else { const int s = (grow - 256) >> 6; r = (grow - 256) & 63; rows = 64; tokbase = TP + s * 4096; }
;         const int rs = min(max(r - 4, 0), rows - 8);
;         const int q0 = j * 16, k0 = min(max(q0 - 8, 0), 32);
;         const size_t qtok = (size_t)tokbase + r * 64 + q0 + l15;
;         const bf16_t* qptr = Qp + qtok * 1024 + h * 128 + l4 * 8;
.LBB0_207:
	s_or_b64 exec, exec, s[0:1]
	s_and_b32 s0, s2, -8
	v_bfe_u32 v65, v144, 4, 2
	v_add_u32_e32 v84, s0, v146
	s_and_b32 s3, s2, 7
	v_lshlrev_b32_e32 v68, 3, v65
	s_movk_i32 s0, 0x800
	v_and_b32_e32 v64, 15, v144
	s_lshl_b32 s24, s3, 7
	v_lshlrev_b32_e32 v69, 2, v65
	v_cmp_gt_i32_e32 vcc, s0, v84
	v_lshlrev_b32_e32 v66, 1, v68
	s_waitcnt lgkmcnt(0)
	s_barrier
	s_and_saveexec_b64 s[4:5], vcc
	s_cbranch_execz .LBB0_338
	s_xor_b32 s8, s3, 7
	s_lshl_b32 s9, s24, 1
	v_lshlrev_b32_e32 v0, 1, v144
	s_add_u32 s0, s88, s9
	v_mov_b32_e32 v71, 0
	s_addc_u32 s1, s89, 0
	v_or_b32_sdwa v70, s24, v64 dst_sel:WORD_1 dst_unused:UNUSED_PAD src0_sel:DWORD src1_sel:DWORD
	v_mov_b32_e32 v67, v71
	v_and_b32_e32 v0, 24, v0
	v_and_or_b32 v85, v144, 3, v0
	v_lshl_add_u64 v[74:75], s[0:1], 0, v[66:67]
	v_bfe_i32 v0, v144, 0, 1
	v_and_b32_e32 v0, 0xfffff840, v0
	v_ashrrev_i32_e32 v1, 31, v0
	v_lshl_add_u64 v[74:75], v[0:1], 0, v[74:75]
	v_lshl_add_u64 v[0:1], s[88:89], 0, v[70:71]
	s_mov_b64 s[0:1], 0x8000000
	v_lshl_add_u64 v[76:77], v[0:1], 0, s[0:1]
	v_lshrrev_b32_e32 v0, 12, v70
	v_mov_b32_e32 v1, 0
	v_lshl_add_u64 v[0:1], s[88:89], 0, v[0:1]
	v_lshl_add_u64 v[76:77], v[0:1], 0, s[0:1]
	v_mbcnt_lo_u32_b32 v0, -1, 0
	v_mbcnt_hi_u32_b32 v0, -1, v0
	v_and_b32_e32 v2, 64, v0
	s_add_u32 s6, s40, s9
	v_xor_b32_e32 v1, 16, v0
	v_add_u32_e32 v2, 64, v2
	s_addc_u32 s7, s41, 0
	s_add_i32 s10, s94, s8
	v_cmp_lt_i32_e32 vcc, v1, v2
	s_add_u32 s8, s36, s9
	s_addc_u32 s9, s37, 0
	v_cndmask_b32_e32 v1, v0, v1, vcc
	v_lshlrev_b32_e32 v86, 2, v1
	v_xor_b32_e32 v1, 32, v0
	s_lshl_b32 s0, s2, 4
	v_cmp_lt_i32_e32 vcc, v1, v2
	s_and_b32 s0, s0, 0xffffff80
	s_mul_i32 s25, s3, 15
	v_lshlrev_b32_e32 v70, 1, v69
	v_cndmask_b32_e32 v0, v0, v1, vcc
	v_lshl_add_u32 v88, v146, 4, s0
	s_lshl_b32 s0, s10, 4
	v_lshl_add_u64 v[72:73], s[8:9], 0, v[66:67]
	s_add_i32 s25, s25, 7
	s_and_b32 s26, s10, -8
	v_lshl_add_u64 v[78:79], s[6:7], 0, v[70:71]
	v_lshlrev_b32_e32 v87, 2, v0
	s_and_b32 s27, s0, 0xffffff80
	s_mov_b64 s[6:7], 0
	s_movk_i32 s42, 0x100
	v_mov_b32_e32 v89, 0xf8
	s_movk_i32 s43, 0x2000
	s_movk_i32 s44, 0x7c
	s_mov_b32 s45, 0xf149f2ca
	s_mov_b32 s46, 0x28000
	s_mov_b32 s47, 0x50000
	s_mov_b32 s48, 0x78000
	s_mov_b32 s49, 0xa0000
	s_mov_b32 s50, 0xc8000
	s_mov_b32 s51, 0xf0000
	s_mov_b32 s56, 0x118000
	s_movk_i32 s57, 0x7ff
	s_branch .LBB0_210

; __device__ __forceinline__ f32x4 mfma16(bf16x8 a, bf16x8 b, f32x4 c) { return __builtin_amdgcn_mfma_f32_16x16x32_bf16(a, b, c, 0, 0, 0); }
; __device__ void phase_na(const Params& P, unsigned char* smem) {
;     ...
;     for (int uu = ((int)blockIdx.x >> 3) * 8 + wid; uu < 2048; uu += nbh * 8) {
;         const int grow = uu >> 2, j = uu & 3;
;         int rows, r, tokbase;
;         if (grow < 256) { rows = 256; r = grow; tokbase = 0; } else { const int s = (grow - 256) >> 6; r = (grow - 256) & 63; rows = 64; tokbase = TP + s * 4096; }
;         const int rs = min(max(r - 4, 0), rows - 8);
;         const int q0 = j * 16, k0 = min(max(q0 - 8, 0), 32);
;         const size_t qtok = (size_t)tokbase + r * 64 + q0 + l15;
;         const bf16_t* qptr = Qp + qtok * 1024 + h * 128 + l4 * 8;
;         bf16x8 qf[4];
; #pragma unroll
;         for (int ks = 0; ks < 4; ++ks) qf[ks] = *(const bf16x8*)(qptr + ks * 32);
;         f32x4 st[8][2];
; #pragma unroll
;         for (int i = 0; i < 8; ++i)
; #pragma unroll
;             for (int a = 0; a < 2; ++a) {
;                 const size_t ktok = (size_t)tokbase + (rs + i) * 64 + k0 + (l15 >> 2) * 8 + a * 4 + (l15 & 3);
;                 const bf16_t* kptr = Kp + ktok * 1024 + h * 128 + l4 * 8;
;                 f32x4 c = {0.f, 0.f, 0.f, 0.f};
; #pragma unroll
;                 for (int ks = 0; ks < 4; ++ks) c = mfma16(*(const bf16x8*)(kptr + ks * 32), qf[ks], c);
;                 st[i][a] = c;
;             }
.LBB0_210:
	v_ashrrev_i32_e32 v0, 2, v84
	v_and_b32_e32 v1, 63, v0
	v_cmp_gt_i32_e32 vcc, s42, v0
	v_lshlrev_b32_e32 v2, 6, v0
	v_and_b32_e32 v2, 0xfffff000, v2
	v_cndmask_b32_e32 v136, v1, v0, vcc
	v_max_i32_e32 v0, 4, v136
	v_and_b32_e32 v137, 48, v88
	v_cndmask_b32_e64 v70, v2, 0, vcc
	v_add_u32_e32 v4, -4, v0
	v_sub_u32_e64 v5, v137, 8 clamp
	v_cndmask_b32_e32 v6, 56, v89, vcc
	v_min_u32_e32 v138, v4, v6
	v_min_u32_e32 v67, 32, v5
	v_or_b32_e32 v4, v70, v85
	v_add_u32_e32 v4, v4, v67
	v_mov_b32_e32 v5, v71
	v_lshlrev_b32_e32 v82, 6, v138
	v_mov_b32_e32 v83, v71
	v_lshlrev_b32_e32 v0, 6, v136
	v_lshl_add_u64 v[6:7], v[82:83], 0, v[4:5]
	v_ashrrev_i32_e32 v1, 31, v0
	v_lshlrev_b64 v[6:7], 11, v[6:7]
	v_lshl_add_u64 v[80:81], v[70:71], 0, v[0:1]
	v_lshl_add_u64 v[60:61], v[74:75], 0, v[6:7]
	v_or_b32_e32 v0, v80, v137
	global_load_dwordx4 v[6:9], v[60:61], off
	v_add_u32_e32 v14, 64, v82
	v_mov_b32_e32 v15, v71
	v_or_b32_e32 v80, v0, v64
	v_lshl_add_u64 v[14:15], v[14:15], 0, v[4:5]
	v_lshlrev_b64 v[0:1], 11, v[80:81]
	v_add_co_u32_e32 v62, vcc, s43, v60
	v_lshlrev_b64 v[14:15], 11, v[14:15]
	v_mov_b32_e32 v19, v71
	v_add_u32_e32 v18, 0x80, v82
	v_lshl_add_u64 v[58:59], v[72:73], 0, v[0:1]
	v_addc_co_u32_e32 v63, vcc, 0, v61, vcc
	v_lshl_add_u64 v[90:91], v[74:75], 0, v[14:15]
	v_lshl_add_u64 v[18:19], v[18:19], 0, v[4:5]
	global_load_dwordx4 v[0:3], v[58:59], off
	v_lshlrev_b64 v[18:19], 11, v[18:19]
	v_add_co_u32_e32 v98, vcc, s43, v90
	v_lshl_add_u64 v[96:97], v[74:75], 0, v[18:19]
	s_nop 0
	v_addc_co_u32_e32 v99, vcc, 0, v91, vcc
	v_add_co_u32_e32 v100, vcc, s43, v96
	global_load_dwordx4 v[10:13], v[62:63], off
	s_nop 0
	v_addc_co_u32_e32 v101, vcc, 0, v97, vcc
	global_load_dwordx4 v[14:17], v[90:91], off
	global_load_dwordx4 v[18:21], v[96:97], off
	global_load_dwordx4 v[22:25], v[98:99], off
	global_load_dwordx4 v[26:29], v[100:101], off
	global_load_dwordx4 v[30:33], v[60:61], off offset:128
	global_load_dwordx4 v[92:95], v[58:59], off offset:64
	global_load_dwordx4 v[34:37], v[62:63], off offset:128
	global_load_dwordx4 v[38:41], v[90:91], off offset:128
	global_load_dwordx4 v[42:45], v[96:97], off offset:128
	global_load_dwordx4 v[46:49], v[98:99], off offset:128
	global_load_dwordx4 v[50:53], v[100:101], off offset:128
	global_load_dwordx4 v[54:57], v[60:61], off offset:2048
	global_load_dwordx4 v[104:107], v[58:59], off offset:128
	s_waitcnt vmcnt(14)
	v_mfma_f32_16x16x32_bf16 v[6:9], v[6:9], v[0:3], 0
	s_waitcnt vmcnt(7)
	v_mfma_f32_16x16x32_bf16 v[6:9], v[30:33], v[92:95], v[6:9]
	global_load_dwordx4 v[30:33], v[62:63], off offset:2048
	v_mfma_f32_16x16x32_bf16 v[10:13], v[10:13], v[0:3], 0
	s_waitcnt vmcnt(7)
	v_mfma_f32_16x16x32_bf16 v[10:13], v[34:37], v[92:95], v[10:13]
	global_load_dwordx4 v[34:37], v[90:91], off offset:2048
	v_mfma_f32_16x16x32_bf16 v[14:17], v[14:17], v[0:3], 0
	v_mfma_f32_16x16x32_bf16 v[18:21], v[18:21], v[0:3], 0
	v_mfma_f32_16x16x32_bf16 v[22:25], v[22:25], v[0:3], 0
	v_mfma_f32_16x16x32_bf16 v[26:29], v[26:29], v[0:3], 0
	s_waitcnt vmcnt(7)
	v_mfma_f32_16x16x32_bf16 v[14:17], v[38:41], v[92:95], v[14:17]
	global_load_dwordx4 v[38:41], v[96:97], off offset:2048
	s_waitcnt vmcnt(7)
	v_mfma_f32_16x16x32_bf16 v[18:21], v[42:45], v[92:95], v[18:21]
	global_load_dwordx4 v[42:45], v[98:99], off offset:2048
	s_waitcnt vmcnt(7)
	v_mfma_f32_16x16x32_bf16 v[22:25], v[46:49], v[92:95], v[22:25]
	global_load_dwordx4 v[46:49], v[100:101], off offset:2048
	s_waitcnt vmcnt(7)
	v_mfma_f32_16x16x32_bf16 v[26:29], v[50:53], v[92:95], v[26:29]
	global_load_dwordx4 v[50:53], v[60:61], off offset:2176
	global_load_dwordx4 v[108:111], v[58:59], off offset:192
	s_waitcnt vmcnt(7)
	v_mfma_f32_16x16x32_bf16 v[6:9], v[54:57], v[104:107], v[6:9]
	global_load_dwordx4 v[54:57], v[62:63], off offset:2176
	s_waitcnt vmcnt(7)
	v_mfma_f32_16x16x32_bf16 v[10:13], v[30:33], v[104:107], v[10:13]
	global_load_dwordx4 v[30:33], v[90:91], off offset:2176
	s_waitcnt vmcnt(7)
	v_mfma_f32_16x16x32_bf16 v[14:17], v[34:37], v[104:107], v[14:17]
	global_load_dwordx4 v[34:37], v[96:97], off offset:2176
	s_waitcnt vmcnt(3)
	v_mfma_f32_16x16x32_bf16 v[60:63], v[50:53], v[108:111], v[6:9]
	s_nop 2
	v_mov_b32_e32 v7, v71
	v_add_u32_e32 v6, 0xc0, v82
	v_lshl_add_u64 v[6:7], v[6:7], 0, v[4:5]
	v_lshlrev_b64 v[6:7], 11, v[6:7]
	s_waitcnt vmcnt(2)
	v_mfma_f32_16x16x32_bf16 v[56:59], v[54:57], v[108:111], v[10:13]
	s_waitcnt vmcnt(1)
	v_mfma_f32_16x16x32_bf16 v[52:55], v[30:33], v[108:111], v[14:17]
	v_lshl_add_u64 v[30:31], v[74:75], 0, v[6:7]
	global_load_dwordx4 v[6:9], v[30:31], off
	global_load_dwordx4 v[10:13], v[30:31], off offset:128
	v_mfma_f32_16x16x32_bf16 v[18:21], v[38:41], v[104:107], v[18:21]
	global_load_dwordx4 v[38:41], v[98:99], off offset:2176
	global_load_dwordx4 v[14:17], v[30:31], off offset:2048
	v_mfma_f32_16x16x32_bf16 v[22:25], v[42:45], v[104:107], v[22:25]
	global_load_dwordx4 v[96:99], v[100:101], off offset:2176
	v_mfma_f32_16x16x32_bf16 v[26:29], v[46:49], v[104:107], v[26:29]
	s_waitcnt vmcnt(5)
	v_mfma_f32_16x16x32_bf16 v[44:47], v[34:37], v[108:111], v[18:21]
	s_nop 2
	global_load_dwordx4 v[18:21], v[30:31], off offset:2176
	s_waitcnt vmcnt(3)
	v_mfma_f32_16x16x32_bf16 v[48:51], v[38:41], v[108:111], v[22:25]
	s_nop 2
	v_add_co_u32_e32 v22, vcc, s43, v30
	v_mfma_f32_16x16x32_bf16 v[6:9], v[6:9], v[0:3], 0
	s_nop 0
	v_addc_co_u32_e32 v23, vcc, 0, v31, vcc
	v_mfma_f32_16x16x32_bf16 v[6:9], v[10:13], v[92:95], v[6:9]
	global_load_dwordx4 v[10:13], v[22:23], off
	s_waitcnt vmcnt(3)
	v_mfma_f32_16x16x32_bf16 v[6:9], v[14:17], v[104:107], v[6:9]
	global_load_dwordx4 v[14:17], v[22:23], off offset:128
	s_waitcnt vmcnt(2)
; __device__ __forceinline__ f32x4 mfma16(bf16x8 a, bf16x8 b, f32x4 c) { return __builtin_amdgcn_mfma_f32_16x16x32_bf16(a, b, c, 0, 0, 0); }
; __device__ void phase_na(const Params& P, unsigned char* smem) {
;     ...
;         for (int ks = 0; ks < 4; ++ks) qf[ks] = *(const bf16x8*)(qptr + ks * 32);
;         f32x4 st[8][2];
; #pragma unroll
;         for (int i = 0; i < 8; ++i)
; #pragma unroll
;             for (int a = 0; a < 2; ++a) {
;                 const size_t ktok = (size_t)tokbase + (rs + i) * 64 + k0 + (l15 >> 2) * 8 + a * 4 + (l15 & 3);
;                 const bf16_t* kptr = Kp + ktok * 1024 + h * 128 + l4 * 8;
;                 f32x4 c = {0.f, 0.f, 0.f, 0.f};
; #pragma unroll
;                 for (int ks = 0; ks < 4; ++ks) c = mfma16(*(const bf16x8*)(kptr + ks * 32), qf[ks], c);
;                 st[i][a] = c;
;             }
;         const int qc = q0 + l15, cs = min(max(qc - 8, 0), 48);
;         float mx = -1e30f;
; #pragma unroll
;         for (int i = 0; i < 8; ++i) {
;             const float* brow = rpb_s + (h * 15 + (rs + i - r + 7)) * 31;
; #pragma unroll
;             for (int a = 0; a < 2; ++a)
; #pragma unroll
;                 for (int jj = 0; jj < 4; ++jj) {
;                     const int kc = k0 + l4 * 8 + a * 4 + jj;
;                     const bool valid = (kc >= cs) && (kc < cs + 16);
;                     const int dc = min(max(kc - qc, -15), 15) + 15;
;                     const float s = valid ? st[i][a][jj] * scale + brow[dc] : -1e30f;
	v_mfma_f32_16x16x32_bf16 v[36:39], v[18:21], v[108:111], v[6:9]
	global_load_dwordx4 v[18:21], v[22:23], off offset:2176
	s_nop 3
	global_load_dwordx4 v[6:9], v[22:23], off offset:2048
	v_mfma_f32_16x16x32_bf16 v[40:43], v[96:99], v[108:111], v[26:29]
	s_waitcnt vmcnt(3)
	v_mfma_f32_16x16x32_bf16 v[10:13], v[10:13], v[0:3], 0
	s_waitcnt vmcnt(2)
	v_mfma_f32_16x16x32_bf16 v[10:13], v[14:17], v[92:95], v[10:13]
	v_add_u32_e32 v14, 0x100, v82
	v_mov_b32_e32 v15, v71
	v_lshl_add_u64 v[14:15], v[14:15], 0, v[4:5]
	v_lshlrev_b64 v[14:15], 11, v[14:15]
	v_lshl_add_u64 v[22:23], v[74:75], 0, v[14:15]
	global_load_dwordx4 v[14:17], v[22:23], off
	s_waitcnt vmcnt(1)
	v_mfma_f32_16x16x32_bf16 v[6:9], v[6:9], v[104:107], v[10:13]
	s_nop 2
	global_load_dwordx4 v[10:13], v[22:23], off offset:128
	v_mfma_f32_16x16x32_bf16 v[32:35], v[18:21], v[108:111], v[6:9]
	global_load_dwordx4 v[18:21], v[22:23], off offset:2176
	s_nop 1
	global_load_dwordx4 v[6:9], v[22:23], off offset:2048
	v_add_co_u32_e32 v22, vcc, s43, v22
	s_waitcnt vmcnt(3)
	v_mfma_f32_16x16x32_bf16 v[14:17], v[14:17], v[0:3], 0
	v_addc_co_u32_e32 v23, vcc, 0, v23, vcc
	s_waitcnt vmcnt(2)
	v_mfma_f32_16x16x32_bf16 v[10:13], v[10:13], v[92:95], v[14:17]
	s_nop 4
	global_load_dwordx4 v[14:17], v[22:23], off
	s_waitcnt vmcnt(1)
	v_mfma_f32_16x16x32_bf16 v[6:9], v[6:9], v[104:107], v[10:13]
	s_nop 2
	global_load_dwordx4 v[10:13], v[22:23], off offset:128
	v_mfma_f32_16x16x32_bf16 v[28:31], v[18:21], v[108:111], v[6:9]
	global_load_dwordx4 v[18:21], v[22:23], off offset:2176
	s_nop 1
	global_load_dwordx4 v[6:9], v[22:23], off offset:2048
	s_waitcnt vmcnt(3)
	v_mfma_f32_16x16x32_bf16 v[14:17], v[14:17], v[0:3], 0
	s_waitcnt vmcnt(2)
	v_mfma_f32_16x16x32_bf16 v[10:13], v[10:13], v[92:95], v[14:17]
	s_nop 5
	v_add_u32_e32 v14, 0x140, v82
	v_mov_b32_e32 v15, v71
	v_lshl_add_u64 v[14:15], v[14:15], 0, v[4:5]
	v_lshlrev_b64 v[14:15], 11, v[14:15]
	v_lshl_add_u64 v[22:23], v[74:75], 0, v[14:15]
	global_load_dwordx4 v[14:17], v[22:23], off
	s_waitcnt vmcnt(1)
	v_mfma_f32_16x16x32_bf16 v[6:9], v[6:9], v[104:107], v[10:13]
	v_add_co_u32_e32 v90, vcc, s43, v22
	s_nop 1
	global_load_dwordx4 v[10:13], v[22:23], off offset:128
	v_mfma_f32_16x16x32_bf16 v[24:27], v[18:21], v[108:111], v[6:9]
	global_load_dwordx4 v[18:21], v[22:23], off offset:2176
	v_addc_co_u32_e32 v91, vcc, 0, v23, vcc
	s_nop 0
	global_load_dwordx4 v[6:9], v[22:23], off offset:2048
	s_waitcnt vmcnt(3)
	v_mfma_f32_16x16x32_bf16 v[14:17], v[14:17], v[0:3], 0
	global_load_dwordx4 v[96:99], v[90:91], off offset:2176
	s_waitcnt vmcnt(3)
	v_mfma_f32_16x16x32_bf16 v[10:13], v[10:13], v[92:95], v[14:17]
	s_nop 4
	global_load_dwordx4 v[14:17], v[90:91], off
	s_waitcnt vmcnt(2)
	v_mfma_f32_16x16x32_bf16 v[6:9], v[6:9], v[104:107], v[10:13]
	s_nop 2
	global_load_dwordx4 v[10:13], v[90:91], off offset:128
	v_mfma_f32_16x16x32_bf16 v[20:23], v[18:21], v[108:111], v[6:9]
	s_nop 2
	global_load_dwordx4 v[6:9], v[90:91], off offset:2048
	s_waitcnt vmcnt(2)
	v_mfma_f32_16x16x32_bf16 v[14:17], v[14:17], v[0:3], 0
	s_waitcnt vmcnt(1)
	v_mfma_f32_16x16x32_bf16 v[10:13], v[10:13], v[92:95], v[14:17]
	s_nop 5
	v_add_u32_e32 v14, 0x180, v82
	v_mov_b32_e32 v15, v71
	v_lshl_add_u64 v[14:15], v[14:15], 0, v[4:5]
	v_lshlrev_b64 v[14:15], 11, v[14:15]
	v_lshl_add_u64 v[14:15], v[74:75], 0, v[14:15]
	global_load_dwordx4 v[100:103], v[14:15], off
	s_waitcnt vmcnt(1)
	v_mfma_f32_16x16x32_bf16 v[6:9], v[6:9], v[104:107], v[10:13]
	v_add_co_u32_e32 v90, vcc, s43, v14
	s_nop 1
	global_load_dwordx4 v[10:13], v[14:15], off offset:128
	v_mfma_f32_16x16x32_bf16 v[16:19], v[96:99], v[108:111], v[6:9]
	v_addc_co_u32_e32 v91, vcc, 0, v15, vcc
	global_load_dwordx4 v[112:115], v[90:91], off offset:128
	s_nop 0
	global_load_dwordx4 v[6:9], v[14:15], off offset:2048
	s_waitcnt vmcnt(3)
	v_mfma_f32_16x16x32_bf16 v[96:99], v[100:103], v[0:3], 0
	global_load_dwordx4 v[100:103], v[14:15], off offset:2176
	s_waitcnt vmcnt(3)
	v_mfma_f32_16x16x32_bf16 v[10:13], v[10:13], v[92:95], v[96:99]
	s_nop 4
	global_load_dwordx4 v[96:99], v[90:91], off
	s_waitcnt vmcnt(2)
	v_mfma_f32_16x16x32_bf16 v[6:9], v[6:9], v[104:107], v[10:13]
	s_nop 2
	v_add_u32_e32 v10, 0x1c0, v82
	v_mov_b32_e32 v11, v71
	v_lshl_add_u64 v[4:5], v[10:11], 0, v[4:5]
	v_lshlrev_b64 v[4:5], 11, v[4:5]
	v_lshl_add_u64 v[10:11], v[74:75], 0, v[4:5]
	s_waitcnt vmcnt(1)
	v_mfma_f32_16x16x32_bf16 v[12:15], v[100:103], v[108:111], v[6:9]
	s_nop 2
	global_load_dwordx4 v[6:9], v[90:91], off offset:2048
	global_load_dwordx4 v[100:103], v[90:91], off offset:2176
	global_load_dwordx4 v[116:119], v[10:11], off
	v_add_co_u32_e32 v90, vcc, s43, v10
	s_waitcnt vmcnt(3)
	v_mfma_f32_16x16x32_bf16 v[96:99], v[96:99], v[0:3], 0
	v_addc_co_u32_e32 v91, vcc, 0, v11, vcc
	v_mfma_f32_16x16x32_bf16 v[96:99], v[112:115], v[92:95], v[96:99]
	global_load_dwordx4 v[112:115], v[10:11], off offset:128
	global_load_dwordx4 v[120:123], v[10:11], off offset:2048
	global_load_dwordx4 v[124:127], v[10:11], off offset:2176
	global_load_dwordx4 v[128:131], v[90:91], off
	s_waitcnt vmcnt(6)
	v_mfma_f32_16x16x32_bf16 v[4:7], v[6:9], v[104:107], v[96:99]
	global_load_dwordx4 v[132:135], v[90:91], off offset:128
	s_nop 1
	v_or_b32_e32 v99, v137, v64
	v_max_i32_e32 v83, 8, v99
	s_waitcnt vmcnt(6)
	v_mfma_f32_16x16x32_bf16 v[8:11], v[100:103], v[108:111], v[4:7]
	v_add_u32_e32 v83, -8, v83
	v_min_u32_e32 v100, 48, v83
	v_sub_u32_e32 v83, s25, v136
	s_waitcnt vmcnt(5)
	v_mfma_f32_16x16x32_bf16 v[4:7], v[116:119], v[0:3], 0
	global_load_dwordx4 v[116:119], v[90:91], off offset:2048
	v_add_u32_e32 v83, v83, v138
	v_add_u32_e32 v101, v67, v68
	s_waitcnt vmcnt(5)
	v_mfma_f32_16x16x32_bf16 v[4:7], v[112:115], v[92:95], v[4:7]
	global_load_dwordx4 v[112:115], v[90:91], off offset:2176
	v_add_u32_e32 v102, 16, v100
	v_mul_lo_u32 v83, v83, s44
	s_waitcnt vmcnt(3)
	v_mfma_f32_16x16x32_bf16 v[0:3], v[128:131], v[0:3], 0
	v_cmp_ge_u32_e32 vcc, v101, v100
	v_cmp_lt_u32_e64 s[0:1], v101, v102
	v_sub_u32_e32 v90, v101, v99
	s_waitcnt vmcnt(2)
	v_mfma_f32_16x16x32_bf16 v[0:3], v[132:135], v[92:95], v[0:3]
	v_add_u32_e32 v91, 0, v83
	s_and_b64 s[8:9], vcc, s[0:1]
	v_mov_b32_e32 v83, 0xf149f2ca
	v_mfma_f32_16x16x32_bf16 v[4:7], v[120:123], v[104:107], v[4:7]
	v_med3_i32 v92, v90, -15, 15
	v_mov_b32_e32 v90, 0xf149f2ca
	s_waitcnt vmcnt(1)
	v_mfma_f32_16x16x32_bf16 v[0:3], v[116:119], v[104:107], v[0:3]
	v_mfma_f32_16x16x32_bf16 v[4:7], v[124:127], v[108:111], v[4:7]
	s_waitcnt vmcnt(0)
	v_mfma_f32_16x16x32_bf16 v[0:3], v[112:115], v[108:111], v[0:3]
	s_and_saveexec_b64 s[0:1], s[8:9]
	s_cbranch_execz .LBB0_212
	v_lshl_add_u32 v90, v92, 2, v91
	ds_read_b32 v90, v90 offset:60
	s_waitcnt lgkmcnt(0)
	v_fmac_f32_e32 v90, 0x3db504f3, v60
